# tail conversion also at the end of MoE gate_up (workgroups >=160, 192 items); PREP of layers>=1 starts 576 items later (4 items per workgroup)
# speedup vs baseline: 1.0137x; 1.0003x over previous
; __device__ __forceinline__ void fp8_convert_range(const Frame& F, int l, int start, int stride, int limit) {
;     ...
;     int it = start;
;     bool ha = it < limit && witem_decode(F, l, it, ta);
;     if (ha) witem_load(ta, F.wave, F.lane, va);
.Lcvt_entry:
	s_lshl_b32 s4, s96, 5
	v_readlane_b32 s0, v250, 32
	s_cmp_lg_u32 s101, 0
	s_cbranch_scc1 .Lcv32_t
	s_cmp_lg_u32 s96, 0
	s_cselect_b32 s1, 9, 0
	s_add_i32 s0, s0, s1
	s_branch .Lcv32_e

; #define LAS __attribute__((address_space(3)))
; __device__ __forceinline__ void witem_load(const WItem& t, int wave, int lane, f32x4 (&v)[16]) {
;     const float* wp = t.W + (size_t)(t.k0 + 32 * wave + 16 * (lane >> 5)) * t.N + t.n0 + 4 * (lane & 31);
; #pragma unroll
;     for (int q = 0; q < 16; ++q) v[q] = __builtin_nontemporal_load((const f32x4*)(wp + (size_t)q * t.N));
; __device__ __forceinline__ void witem_store(const Frame& F, const WItem& t, const f32x4 (&v)[16], LAS unsigned char* tile) {
;     const int i = F.lane & 31, hi = F.lane >> 5;
; #pragma unroll
;     for (int j = 0; j < 4; ++j) {
;         u32x4 o;
; #pragma unroll
;         for (int d = 0; d < 4; ++d) { int r = __builtin_amdgcn_cvt_pk_fp8_f32(v[4 * d][j] * t.scale, v[4 * d + 1][j] * t.scale, 0, false);
;             r = __builtin_amdgcn_cvt_pk_fp8_f32(v[4 * d + 2][j] * t.scale, v[4 * d + 3][j] * t.scale, r, true); o[d] = (unsigned)r; }
;         *(LAS u32x4*)(tile + (32 * j + i) * 272 + 32 * F.wave + 16 * hi) = o;
;     }
;     __syncthreads();
;     const int c = F.tid & 15;
; #pragma unroll
;     for (int pass = 0; pass < 4; ++pass) { const int n = (F.tid >> 4) + 32 * pass, rho = (n & 3) * 32 + (n >> 2);
;         const u32x4 o = *(const LAS u32x4*)(tile + rho * 272 + 16 * c);
.Lcv34_e:
	v_sub_f32_e32 v1, v1, v3
	v_floor_f32_e32 v1, v1
	v_cmp_gt_f32_e32 vcc, s6, v1
	s_and_b64 s[6:7], vcc, exec
	s_cselect_b32 s7, 0xffffffc0, 0
	s_lshl_b32 s6, s8, 5
	s_add_i32 s8, s6, s9
	v_or_b32_e32 v2, s8, v54
	v_ashrrev_i32_e32 v3, 31, v2
	v_lshlrev_b64 v[2:3], 13, v[2:3]
	v_lshl_add_u64 v[2:3], s[26:27], 0, v[2:3]
	v_lshl_add_u64 v[2:3], s[44:45], 2, v[2:3]
	v_lshl_add_u64 v[38:39], v[2:3], 0, v[198:199]
	v_cndmask_b32_e32 v55, 0, v233, vcc
	v_add_co_u32_e32 v6, vcc, s70, v38
	s_movk_i32 s8, 0x4000
	s_nop 0
	v_addc_co_u32_e32 v7, vcc, 0, v39, vcc
	v_add_co_u32_e32 v10, vcc, s8, v38
	s_movk_i32 s8, 0x6000
	s_nop 0
	v_addc_co_u32_e32 v11, vcc, 0, v39, vcc
	v_add_co_u32_e32 v14, vcc, s8, v38
	s_mov_b32 s8, 0x8000
	s_nop 0
	v_addc_co_u32_e32 v15, vcc, 0, v39, vcc
	v_add_co_u32_e32 v18, vcc, s8, v38
	s_mov_b32 s8, 0xa000
	s_nop 0
	v_addc_co_u32_e32 v19, vcc, 0, v39, vcc
	v_add_co_u32_e32 v22, vcc, s8, v38
	s_mov_b32 s8, 0xc000
	s_nop 0
	v_addc_co_u32_e32 v23, vcc, 0, v39, vcc
	v_add_co_u32_e32 v26, vcc, s8, v38
	s_mov_b32 s8, 0xe000
	s_nop 0
	v_addc_co_u32_e32 v27, vcc, 0, v39, vcc
	v_add_co_u32_e32 v30, vcc, s8, v38
	s_mov_b32 s8, 0x12000
	s_nop 0
	v_addc_co_u32_e32 v31, vcc, 0, v39, vcc
	v_add_co_u32_e32 v34, vcc, s71, v38
	v_add_f32_e32 v1, v1, v55
	s_nop 0
	v_addc_co_u32_e32 v35, vcc, 0, v39, vcc
	v_add_co_u32_e32 v40, vcc, s8, v38
	s_mov_b32 s8, 0x14000
	s_nop 0
	v_addc_co_u32_e32 v41, vcc, 0, v39, vcc
	v_add_co_u32_e32 v42, vcc, s8, v38
	s_mov_b32 s8, 0x16000
	s_nop 0
	v_addc_co_u32_e32 v43, vcc, 0, v39, vcc
	v_add_co_u32_e32 v44, vcc, s8, v38
	s_mov_b32 s8, 0x18000
	s_nop 0
	v_addc_co_u32_e32 v45, vcc, 0, v39, vcc
	v_add_co_u32_e32 v46, vcc, s8, v38
	s_mov_b32 s8, 0x1a000
	s_nop 0
	v_addc_co_u32_e32 v47, vcc, 0, v39, vcc
	v_add_co_u32_e32 v48, vcc, s8, v38
	s_mov_b32 s8, 0x1c000
	s_nop 0
	v_addc_co_u32_e32 v49, vcc, 0, v39, vcc
	global_load_dwordx4 v[2:5], v[38:39], off nt
	s_nop 0
	global_load_dwordx4 v[6:9], v[6:7], off nt
	s_nop 0
	global_load_dwordx4 v[10:13], v[10:11], off nt
	s_nop 0
	global_load_dwordx4 v[14:17], v[14:15], off nt
	s_nop 0
	global_load_dwordx4 v[18:21], v[18:19], off nt
	s_nop 0
	global_load_dwordx4 v[22:25], v[22:23], off nt
	s_nop 0
	global_load_dwordx4 v[26:29], v[26:27], off nt
	s_nop 0
	global_load_dwordx4 v[30:33], v[30:31], off nt
	s_nop 0
	global_load_dwordx4 v[34:37], v[34:35], off nt
	s_nop 0
	global_load_dwordx4 v[50:53], v[40:41], off nt
	global_load_dwordx4 v[62:65], v[42:43], off nt
	global_load_dwordx4 v[70:73], v[44:45], off nt
	global_load_dwordx4 v[82:85], v[46:47], off nt
	global_load_dwordx4 v[86:89], v[48:49], off nt
	v_add_co_u32_e32 v40, vcc, s8, v38
	s_mov_b32 s8, 0x1e000
	s_nop 0
	v_addc_co_u32_e32 v41, vcc, 0, v39, vcc
	v_add_co_u32_e32 v38, vcc, s8, v38
	v_exp_f32_e32 v1, v1
	s_nop 0
	v_addc_co_u32_e32 v39, vcc, 0, v39, vcc
	global_load_dwordx4 v[94:97], v[40:41], off nt
	global_load_dwordx4 v[102:105], v[38:39], off nt
	v_ldexp_f32 v146, v1, s7
	v_or_b32_e32 v1, s6, v54
	s_add_i32 s6, s6, 0
	v_and_b32_e32 v38, 31, v0
	v_mov_b32_e32 v39, s6
	s_movk_i32 s6, 0x110
	v_lshlrev_b32_e32 v40, 5, v131
	v_mad_u32_u24 v38, v38, s6, v39
	v_lshlrev_b32_e32 v39, 4, v0
	v_and_b32_e32 v40, 0x60, v40
	v_ashrrev_i32_e32 v41, 6, v0
	v_lshrrev_b32_e32 v45, 2, v134
	v_lshrrev_b32_e32 v48, 2, v135
	v_and_b32_e32 v132, 0xf0, v39
	v_add_u32_e32 v41, v40, v41
	v_lshlrev_b32_e32 v42, 2, v131
	v_lshrrev_b32_e32 v43, 1, v131
	v_add_u32_e32 v45, v40, v45
	v_lshlrev_b32_e32 v46, 2, v134
	v_add_u32_e32 v48, v40, v48
	v_lshlrev_b32_e32 v49, 2, v135
	v_add_u32_e32 v40, v40, v56
	v_lshlrev_b32_e32 v56, 2, v136
	v_add_u32_e32 v39, 0, v132
	v_mul_lo_u32 v41, v41, s6
	v_and_b32_e32 v42, 16, v42
	v_and_b32_e32 v43, 12, v43
	v_and_b32_e32 v44, 0x63, v131
	v_mul_lo_u32 v45, v45, s6
	v_and_b32_e32 v46, 16, v46
	v_and_b32_e32 v47, 0x63, v134
	v_mul_lo_u32 v48, v48, s6
	v_and_b32_e32 v49, 16, v49
	v_and_b32_e32 v55, 0x63, v135
	v_mul_lo_u32 v40, v40, s6
	v_and_b32_e32 v56, 16, v56
	v_or3_b32 v137, v42, v44, v43
	v_or3_b32 v138, v47, v46, v43
	v_or3_b32 v139, v55, v49, v43
	v_or3_b32 v140, v57, v56, v43
	v_add_u32_e32 v141, v38, v54
	v_add_u32_e32 v142, v39, v41
	v_add_u32_e32 v143, v39, v45
	v_add_u32_e32 v144, v39, v48
	v_add_u32_e32 v145, v39, v40
	v_readlane_b32 s6, v250, 33
	s_cmp_lg_u32 s101, 0
	s_cbranch_scc1 .Lcv33_t
	s_cmp_lg_u32 s96, 0
	s_cselect_b32 s7, 0x240, 0
	s_add_i32 s6, s6, s7
	s_branch .Lcv33_e

; #define SEAM(k) do { if (IN(k) && IN((k) + 1)) xcd_barrier(bar, is_t0); } while (0)
; __device__ __forceinline__ void xcd_barrier(const XcdBarrier& b, const bool is_t0) {
;     asm volatile("s_waitcnt vmcnt(0)" ::: "memory");
;     __syncthreads();
;     if (is_t0) {
;         unsigned* bar = b.bar;
;         __builtin_amdgcn_s_waitcnt(0);
;         unsigned nloc = b.st[0], nx = b.st[1];
;         if (nloc == 0u) { xcd_barrier_complete(bar, b.x, nloc, nx); b.st[0] = nloc; b.st[1] = nx; }
; __global__ void __launch_bounds__(NTHR, 2) fwd(Args args) {
;     ...
;         if ((PMASK & 128) && IN(pb + 5)) { for (int rep = 0; rep < REPS(128); ++rep) { F = launder(F); phase_moe<0>(F, l); if (REPS(128) > 1) __syncthreads(); } SEAM(pb + 5); }
.LBB0_2254:
	s_cmp_lt_u32 s80, 0xa0
	s_cbranch_scc1 .Ltc_skip2
	s_cmp_gt_u32 s96, 2
	s_cbranch_scc1 .Ltc_skip2
	s_sub_i32 s0, s80, 0xa0
	s_add_i32 s0, s0, 0x180
	s_lshr_b32 s1, s0, 6
	s_and_b32 s3, s0, 63
	s_lshr_b32 s4, s3, 4
	s_lshl_b32 s4, s4, 8
	s_and_b32 s3, s3, 15
	s_lshl_b32 s3, s3, 7
	s_mov_b32 s5, 0
	v_writelane_b32 v248, s1, 41
	v_writelane_b32 v248, s0, 42
	v_writelane_b32 v248, s4, 43
	v_writelane_b32 v248, s3, 44
	v_writelane_b32 v248, s5, 45
	s_add_i32 s96, s96, 1
	s_lshl_b32 s28, s96, 1
	s_mov_b32 s29, 0
	s_movk_i32 s74, 0x60
	s_movk_i32 s70, 0x2000
	s_mov_b32 s71, 0x10000
	v_readfirstlane_b32 s8, v0
	s_ashr_i32 s8, s8, 6
	v_and_b32_e32 v66, 63, v0
	v_lshlrev_b32_e32 v66, 2, v66
	s_movk_i32 s100, 0x240
	s_mov_b32 s101, 2
	s_mov_b64 exec, -1
	s_branch .Lcvt_entry
.Ltc_ret2:
	s_mov_b32 s101, 0
	s_sub_i32 s96, s96, 1
	v_readlane_b32 s28, v249, 44
	v_readlane_b32 s29, v249, 45
	v_readlane_b32 s74, v249, 46
	s_movk_i32 s70, 0x2000
	s_mov_b32 s71, 0x10000
	v_readlane_b32 s0, v250, 56
	v_readlane_b32 s1, v250, 57
	s_nop 1
	v_cndmask_b32_e64 v1, 0, 1, s[0:1]
	v_cmp_ne_u32_e64 s[36:37], 1, v1
.Ltc_skip2:
	v_readlane_b32 s0, v249, 55
	s_add_i32 s3, s0, 8
	v_readlane_b32 s4, v251, 8
	v_readlane_b32 s5, v251, 9
	s_cmp_gt_i32 s4, s3
	s_cselect_b64 s[0:1], -1, 0
	s_cmp_ge_i32 s3, s5
	s_cselect_b64 s[4:5], -1, 0
	s_or_b64 s[0:1], s[0:1], s[4:5]
	s_and_b64 vcc, exec, s[0:1]
	s_cbranch_vccnz .LBB0_2266
	s_waitcnt vmcnt(0)
	s_waitcnt vmcnt(0)
	s_barrier
	s_mov_b64 s[0:1], exec
	v_readlane_b32 s4, v251, 6
	v_readlane_b32 s5, v251, 7
	v_readlane_b32 s28, v249, 44
	s_and_b64 s[4:5], s[0:1], s[4:5]
	v_readlane_b32 s29, v249, 45
	s_mov_b64 exec, s[4:5]
	s_cbranch_execz .LBB0_2304
	v_readlane_b32 s4, v249, 33
	s_waitcnt vmcnt(0) expcnt(0) lgkmcnt(0)
	s_nop 0
	v_mov_b32_e32 v1, s4
	ds_read_b32 v3, v1
	v_readlane_b32 s4, v249, 34
	s_waitcnt lgkmcnt(0)
	v_cmp_ne_u32_e32 vcc, 0, v3
	v_mov_b32_e32 v1, s4
	ds_read_b32 v2, v1
	s_cbranch_vccnz .LBB0_2272
	v_readlane_b32 s6, v251, 4
	v_readlane_b32 s7, v251, 5
	s_load_dwordx2 s[4:5], s[6:7], 0x4
	s_mov_b32 s11, 1
	s_waitcnt lgkmcnt(0)
	s_mul_i32 s10, s4, s81
	s_mul_i32 s10, s10, s5
	s_branch .LBB0_2259

; #define SEAM(k) do { if (IN(k) && IN((k) + 1)) xcd_barrier(bar, is_t0); } while (0)
; __device__ __forceinline__ void fp8_convert_range(const Frame& F, int l, int start, int stride, int limit) {
;     __syncthreads();
;     WItem ta, tb; f32x4 va[16], vb[16];
;     int it = start;
;     bool ha = it < limit && witem_decode(F, l, it, ta);
;     if (ha) witem_load(ta, F.wave, F.lane, va);
; __global__ void __launch_bounds__(NTHR, 2) fwd(Args args) {
;     ...
;         if ((PMASK & 256) && IN(pb + 6)) { for (int rep = 0; rep < REPS(256); ++rep) { F = launder(F); phase_moe<1>(F, l); if (REPS(256) > 1) __syncthreads(); } SEAM(pb + 6); }
.LBB0_2367:
	s_cmp_lt_u32 s80, 0x80
	s_cbranch_scc1 .Ltc_skip1
	s_cmp_gt_u32 s96, 2
	s_cbranch_scc1 .Ltc_skip1
	s_sub_i32 s0, s80, 0x80
	s_add_i32 s0, s0, 0x0
	s_lshr_b32 s1, s0, 6
	s_and_b32 s3, s0, 63
	s_lshr_b32 s4, s3, 4
	s_lshl_b32 s4, s4, 8
	s_and_b32 s3, s3, 15
	s_lshl_b32 s3, s3, 7
	s_mov_b32 s5, 0
	v_writelane_b32 v248, s1, 41
	v_writelane_b32 v248, s0, 42
	v_writelane_b32 v248, s4, 43
	v_writelane_b32 v248, s3, 44
	v_writelane_b32 v248, s5, 45
	s_add_i32 s96, s96, 1
	s_lshl_b32 s28, s96, 1
	s_mov_b32 s29, 0
	s_movk_i32 s74, 0x80
	s_movk_i32 s70, 0x2000
	s_mov_b32 s71, 0x10000
	v_readfirstlane_b32 s8, v0
	s_ashr_i32 s8, s8, 6
	v_and_b32_e32 v66, 63, v0
	v_lshlrev_b32_e32 v66, 2, v66
	s_movk_i32 s100, 0x180
	s_mov_b32 s101, 1
	s_mov_b64 exec, -1
	s_branch .Lcvt_entry
.Ltc_ret:
	s_cmp_eq_u32 s101, 2
	s_cbranch_scc1 .Ltc_ret2
